# xattn: L2 warm-up of stages 2..7 K/V chunks via dummy loads at unit start (on O2 selection rewrite, without the ds_read ring)
# baseline (speedup 1.0000x reference)
; #define LAS __attribute__((address_space(3)))
; template <int DQK, int DV, int MODE, bool QNORM, int SK, int NQ> ...
;     ...
;             sscale[qh] = qk_scale * __builtin_amdgcn_rsqf(ss * (1.0f / DQK) + EPS);
;         }
;     }
;     float m_run[NQ], l_run[NQ];
; #pragma unroll
;     for (int qh = 0; qh < NQ; ++qh) {
;         m_run[qh] = 0.f; l_run[qh] = 0.f;
; #pragma unroll
;         for (int dt = 0; dt < DV / 32; ++dt)
; #pragma unroll
;             for (int r = 0; r < 16; ++r) o[qh][dt][r] = 0.f;
;     }
;     int goff[NLD]; bool isk[NLD]; int gstep[NLD]; int ldst[NLD]; bool act[NLD];
; #pragma unroll
;     for (int i = 0; i < NLD; ++i) {
;         const int c = tid + i * 512; act[i] = c < NCH;
;         isk[i] = c < KCH;
;         if (c < KCH) { const int row = c / KCPR, ch = c % KCPR; goff[i] = row * k_pitch + ch * 8; gstep[i] = SK * k_pitch; ldst[i] = row * KP + ch * 16; }
;         else { const int c2 = c - KCH, row = c2 / VCPR, ch = c2 % VCPR; goff[i] = (row < DV ? row : 0) * vt_pitch + ch * 8; gstep[i] = SK; ldst[i] = KBYTES + row * VP + ch * 16; }
;     }
;     constexpr bool PF2 = (NQ == 1 && DQK <= 96);
;     u32x4 stg[NLD], stg2[NLD];
;     const int nstage = (nst + NSUB - 1) / NSUB;
; #pragma unroll
;     for (int i = 0; i < NLD; ++i) if (act[i]) stg2[i] = *(const u32x4*)((isk[i] ? Kp : Vt) + goff[i]);
;     if (PF2 && 1 < nstage) {
; #pragma unroll
;         for (int i = 0; i < NLD; ++i) if (act[i]) stg[i] = *(const u32x4*)((isk[i] ? Kp : Vt) + goff[i] + gstep[i]);
;     }
; #pragma unroll
;     for (int i = 0; i < NLD; ++i) if (act[i]) *(LAS u32x4*)(lds + ldst[i]) = stg2[i];
;     unsigned wcur0 = 0xffffffffu, wcur1 = 0xffffffffu;
;     const unsigned* mrow = (MODE == 1) ? (mw + (size_t)r32 * 64) : nullptr;
;     if (MODE == 1) { wcur0 = mrow[0]; wcur1 = (NSUB > 1 && 1 < nst) ? mrow[1] : 0u; }
;     __syncthreads();
.LBB0_4649:
	s_or_b64 exec, exec, s[16:17]
	s_waitcnt lgkmcnt(0)
	v_add_f32_e32 v1, v1, v14
	v_fmamk_f32 v1, v1, 0x3b800000, v231
	v_rsq_f32_e32 v1, v1
	v_mov_b32_e32 v6, s13
	v_mov_b32_e32 v7, s14
	v_mov_b32_e32 v8, s12
	v_mul_f32_e32 v170, 0x3db8aa3b, v1
	v_mov_b32_e32 v1, s15
	v_cndmask_b32_e64 v5, v1, v6, s[6:7]
	v_cndmask_b32_e64 v4, v7, v8, s[6:7]
	v_lshl_add_u64 v[176:177], v[160:161], 1, v[2:3]
	v_cndmask_b32_e64 v3, v1, v6, s[10:11]
	v_cndmask_b32_e64 v2, v7, v8, s[10:11]
	v_mov_b32_e32 v14, v0
	v_mov_b32_e32 v15, v0
	v_lshl_add_u64 v[174:175], v[158:159], 1, v[4:5]
	v_lshl_add_u64 v[178:179], v[162:163], 1, v[2:3]
	v_mov_b32_e32 v1, v0
	v_mov_b32_e32 v2, v0
	v_mov_b32_e32 v3, v0
	v_mov_b32_e32 v4, v0
	v_mov_b32_e32 v5, v0
	v_mov_b32_e32 v6, v0
	v_mov_b32_e32 v7, v0
	v_mov_b32_e32 v8, v0
	v_mov_b32_e32 v9, v0
	v_mov_b32_e32 v10, v0
	v_mov_b32_e32 v11, v0
	v_mov_b32_e32 v12, v0
	v_mov_b32_e32 v13, v0
	v_mov_b64_e32 v[64:65], v[14:15]
	v_mov_b64_e32 v[48:49], v[14:15]
	v_mov_b64_e32 v[32:33], v[14:15]
	v_mov_b64_e32 v[62:63], v[12:13]
	v_mov_b64_e32 v[60:61], v[10:11]
	v_mov_b64_e32 v[58:59], v[8:9]
	v_mov_b64_e32 v[56:57], v[6:7]
	v_mov_b64_e32 v[54:55], v[4:5]
	v_mov_b64_e32 v[52:53], v[2:3]
	v_mov_b64_e32 v[50:51], v[0:1]
	v_mov_b64_e32 v[46:47], v[12:13]
	v_mov_b64_e32 v[44:45], v[10:11]
	v_mov_b64_e32 v[42:43], v[8:9]
	v_mov_b64_e32 v[40:41], v[6:7]
	v_mov_b64_e32 v[38:39], v[4:5]
	v_mov_b64_e32 v[36:37], v[2:3]
	v_mov_b64_e32 v[34:35], v[0:1]
	v_mov_b64_e32 v[30:31], v[12:13]
	v_mov_b64_e32 v[28:29], v[10:11]
	v_mov_b64_e32 v[26:27], v[8:9]
	v_mov_b64_e32 v[24:25], v[6:7]
	v_mov_b64_e32 v[22:23], v[4:5]
	v_mov_b64_e32 v[20:21], v[2:3]
	v_mov_b64_e32 v[18:19], v[0:1]
	v_mov_b64_e32 v[16:17], v[14:15]
	s_lshl_b32 s16, s27, 8
	v_mov_b32_e32 v171, v170
	s_mov_b32 s15, 0
	v_mov_b32_e32 v165, 0
	v_mov_b64_e32 v[14:15], v[12:13]
	v_mov_b64_e32 v[12:13], v[10:11]
	v_mov_b64_e32 v[10:11], v[8:9]
	v_mov_b64_e32 v[8:9], v[6:7]
	v_mov_b64_e32 v[6:7], v[4:5]
	v_mov_b64_e32 v[4:5], v[2:3]
	v_mov_b64_e32 v[2:3], v[0:1]
	v_mov_b32_e32 v172, 0
	s_barrier
	s_and_saveexec_b64 s[12:13], s[4:5]
	v_lshlrev_b32_e64 v66, v187, 2
	v_mov_b32_e32 v67, v0
	v_lshl_add_u64 v[66:67], v[66:67], 1, v[174:175]
	global_load_dwordx4 v[216:219], v[66:67], off
	v_lshlrev_b32_e64 v66, v187, 3
	v_mov_b32_e32 v67, v0
	v_lshl_add_u64 v[66:67], v[66:67], 1, v[174:175]
	global_load_dwordx4 v[216:219], v[66:67], off
	v_lshlrev_b32_e64 v66, v187, 4
	v_mov_b32_e32 v67, v0
	v_lshl_add_u64 v[66:67], v[66:67], 1, v[174:175]
	global_load_dwordx4 v[216:219], v[66:67], off
	v_lshlrev_b32_e64 v66, v187, 5
	v_mov_b32_e32 v67, v0
	v_lshl_add_u64 v[66:67], v[66:67], 1, v[174:175]
	global_load_dwordx4 v[216:219], v[66:67], off
	v_lshlrev_b32_e64 v66, v187, 6
	v_mov_b32_e32 v67, v0
	v_lshl_add_u64 v[66:67], v[66:67], 1, v[174:175]
	global_load_dwordx4 v[216:219], v[66:67], off
	v_lshlrev_b32_e64 v66, v187, 7
	v_mov_b32_e32 v67, v0
	v_lshl_add_u64 v[66:67], v[66:67], 1, v[174:175]
	global_load_dwordx4 v[216:219], v[66:67], off
	s_or_b64 exec, exec, s[12:13]
	s_and_saveexec_b64 s[12:13], s[6:7]
	v_lshlrev_b32_e64 v66, v188, 2
	v_mov_b32_e32 v67, v0
	v_lshl_add_u64 v[66:67], v[66:67], 1, v[176:177]
	global_load_dwordx4 v[216:219], v[66:67], off
	v_lshlrev_b32_e64 v66, v188, 3
	v_mov_b32_e32 v67, v0
	v_lshl_add_u64 v[66:67], v[66:67], 1, v[176:177]
	global_load_dwordx4 v[216:219], v[66:67], off
	v_lshlrev_b32_e64 v66, v188, 4
	v_mov_b32_e32 v67, v0
	v_lshl_add_u64 v[66:67], v[66:67], 1, v[176:177]
	global_load_dwordx4 v[216:219], v[66:67], off
	v_lshlrev_b32_e64 v66, v188, 5
	v_mov_b32_e32 v67, v0
	v_lshl_add_u64 v[66:67], v[66:67], 1, v[176:177]
	global_load_dwordx4 v[216:219], v[66:67], off
	v_lshlrev_b32_e64 v66, v188, 6
	v_mov_b32_e32 v67, v0
	v_lshl_add_u64 v[66:67], v[66:67], 1, v[176:177]
	global_load_dwordx4 v[216:219], v[66:67], off
	v_lshlrev_b32_e64 v66, v188, 7
	v_mov_b32_e32 v67, v0
	v_lshl_add_u64 v[66:67], v[66:67], 1, v[176:177]
	global_load_dwordx4 v[216:219], v[66:67], off
	s_or_b64 exec, exec, s[12:13]
	s_and_saveexec_b64 s[12:13], s[8:9]
	v_lshlrev_b32_e64 v66, v189, 2
	v_mov_b32_e32 v67, v0
	v_lshl_add_u64 v[66:67], v[66:67], 1, v[178:179]
	global_load_dwordx4 v[216:219], v[66:67], off
	v_lshlrev_b32_e64 v66, v189, 3
	v_mov_b32_e32 v67, v0
	v_lshl_add_u64 v[66:67], v[66:67], 1, v[178:179]
	global_load_dwordx4 v[216:219], v[66:67], off
	v_lshlrev_b32_e64 v66, v189, 4
	v_mov_b32_e32 v67, v0
	v_lshl_add_u64 v[66:67], v[66:67], 1, v[178:179]
	global_load_dwordx4 v[216:219], v[66:67], off
	v_lshlrev_b32_e64 v66, v189, 5
	v_mov_b32_e32 v67, v0
	v_lshl_add_u64 v[66:67], v[66:67], 1, v[178:179]
	global_load_dwordx4 v[216:219], v[66:67], off
	v_lshlrev_b32_e64 v66, v189, 6
	v_mov_b32_e32 v67, v0
	v_lshl_add_u64 v[66:67], v[66:67], 1, v[178:179]
	global_load_dwordx4 v[216:219], v[66:67], off
	v_lshlrev_b32_e64 v66, v189, 7
	v_mov_b32_e32 v67, v0
	v_lshl_add_u64 v[66:67], v[66:67], 1, v[178:179]
	global_load_dwordx4 v[216:219], v[66:67], off
	s_or_b64 exec, exec, s[12:13]
	s_add_i32 s14, s15, 1
	s_and_saveexec_b64 s[12:13], s[4:5]
	s_cbranch_execnz .LBB0_4661
